# attention phase: one static s_setprio 1 for waves 4-7 at phase entry (reset at exit); on top of the GEMM K-loop edits
# baseline (speedup 1.0000x reference)
; __device__ __forceinline__ int tidx() { int t = threadIdx.x; asm volatile("" : "+v"(t)); return t; }
; #define LAS __attribute__((address_space(3)))
; __device__ __forceinline__ int att_jlo(int L, int pass, const float* NRM, const float* FK, LAS unsigned char* lds, int tid, int lane, int wave) {
;     ...
;     if (tid < 256) { const f32x4 v = *(const f32x4*)(NQ + (size_t)(P0 + tid) * 4); kq = (v[0] + v[1]) + (v[2] + v[3]); }
; __device__ __forceinline__ void attn_phase(const hbf* Q, const hbf* K, const hbf* V, hbf* O, const float* FK, const float* NRM, char* lds) {
;     constexpr int total = 8 * BATCH * NH, W = 1 << 30;
;     const int stride = gridDim.x; int L = blockIdx.x; if (L >= total) return;
;     const int L0 = L;
;     int jl0, jl1, jl2 = 0, jl3 = 0;
;     { const int tid = tidx(), lane = tid & 63, wave = __builtin_amdgcn_readfirstlane(tid >> 6);
;       jl0 = att_jlo(L0, 0, NRM, FK, (LAS unsigned char*)lds, tid, lane, wave); jl1 = att_jlo(L0, 1, NRM, FK, (LAS unsigned char*)lds, tid, lane, wave);
;       if (L0 + stride < total) { jl2 = att_jlo(L0 + stride, 0, NRM, FK, (LAS unsigned char*)lds, tid, lane, wave); jl3 = att_jlo(L0 + stride, 1, NRM, FK, (LAS unsigned char*)lds, tid, lane, wave); } }
.LBB0_162:
	s_andn2_b64 vcc, exec, s[26:27]
	s_cbranch_vccnz .LBB0_380
	v_readlane_b32 s14, v253, 9
	v_readlane_b32 s15, v253, 10
	s_andn2_b64 vcc, exec, s[14:15]
	s_cbranch_vccnz .LBB0_380
	s_waitcnt lgkmcnt(0)
	s_add_u32 s7, s54, 0x24600000
	s_addc_u32 s8, s55, 0
	v_readlane_b32 s14, v254, 48
	v_mov_b32_e32 v0, v238
	v_readlane_b32 s15, v254, 49
	s_add_u32 s14, s7, s14
	s_movk_i32 s12, 0x100
	s_addc_u32 s15, s8, s15
	v_readfirstlane_b32 s2, v0
	s_nop 3
	s_cmp_ge_u32 s2, 0x100
	s_cbranch_scc0 .Lattn_prio_done
	s_setprio 1
.Lattn_prio_done:
	v_cmp_gt_i32_e64 s[42:43], s12, v0
	v_mov_b32_e32 v4, 0
	v_mov_b32_e32 v5, 0
	s_and_saveexec_b64 s[22:23], s[42:43]
	s_cbranch_execz .LBB0_166
	v_readlane_b32 s12, v253, 13
	s_nop 1
	v_add_u32_e32 v2, s12, v0
	v_ashrrev_i32_e32 v3, 31, v2
	v_lshl_add_u64 v[2:3], v[2:3], 4, s[14:15]
	global_load_dwordx4 v[6:9], v[2:3], off
	s_waitcnt vmcnt(0)
	v_mov_b32_e32 v2, v7
	v_mov_b32_e32 v3, v8
	v_mov_b32_e32 v7, v9
	v_pk_add_f32 v[2:3], v[2:3], v[6:7]
	s_nop 0
	v_add_f32_e32 v5, v2, v3

; __device__ __forceinline__ void attn_phase(const hbf* Q, const hbf* K, const hbf* V, hbf* O, const float* FK, const float* NRM, char* lds) {
;     ...
;     for (;;) {
;         const bool more_pass = pass == 0, more_item = (L == L0) && (L + stride < total), last = !more_pass && !more_item;
;         int passn = pass + 1, Ln = L;
;         if (!more_pass) { passn = 0; Ln = more_item ? L + stride : L; }
;         const int jn = (Ln == L0) ? (passn ? jl1 : jl0) : (passn ? jl3 : jl2);
;         const att::BlockRef<hbf, hbf> nxt = last ? cur : att_ref(Ln, passn, jn, Q, K, V, O, FK);
;         att::causal_swa_block<hbf, hbf>(cur, nxt, SEQ, W, lds, S, lds + att::ATT_F_OFF + fsel * 16384, lds + att::ATT_F_OFF + (fsel ^ 1) * 16384);
;         if (last) break;
;         cur = nxt; pass = passn; L = Ln; fsel ^= 1;
;     }
.LBB0_377:
	s_or_b64 exec, exec, s[26:27]
	s_andn2_b64 vcc, exec, s[24:25]
	s_mov_b32 s12, 1
	s_waitcnt lgkmcnt(0)
	s_barrier
	s_cbranch_vccnz .LBB0_207
	s_xor_b32 s12, s71, 1
	s_mov_b32 s76, s21
	s_mov_b64 s[38:39], s[60:61]
	s_mov_b64 s[46:47], s[54:55]
	s_mov_b64 s[52:53], s[36:37]
	s_mov_b64 s[50:51], s[66:67]
	s_mov_b64 s[14:15], s[44:45]
	s_mov_b32 s8, s20
	s_mov_b32 s92, s7
	s_mov_b32 s70, s2
	s_branch .LBB0_207
	s_nop 0
	s_nop 0
	s_nop 0
	s_nop 0
	s_nop 0
	s_nop 0
	s_nop 0
	s_nop 0
	s_nop 0
	s_nop 0

; __global__ void __launch_bounds__(NTHREADS, 2) fwd_mega(Args a) {
;     ...
;         } else if (KEN(K_ATTN) && kind == K_ATTN) {
;             attn_phase((const hbf*)Qb, (const hbf*)Kb, (const hbf*)Vb, (hbf*)Ob, FK, (const float*)(ws + WS_NRM), (char*)lds);
.LBB0_380:
	s_setprio 0
	s_mov_b64 s[36:37], 0
